# LDS-DMA SGPR-base addressing also in resid and mixin K-loops
# speedup vs baseline: 1.0256x; 1.0050x over previous
.LBB0_328:
	s_ashr_i32 s31, s30, 31
	s_lshl_b64 s[34:35], s[30:31], 19
	s_add_u32 s34, s84, s34
	s_addc_u32 s35, s85, s35
	s_and_b64 s[38:39], s[4:5], exec
	s_cselect_b32 s7, s35, s93
	s_cselect_b32 s11, s34, s92
	s_ashr_i32 s29, s28, 31
	s_lshl_b64 s[38:39], s[28:29], 19
	s_add_u32 s38, s56, s38
	s_addc_u32 s39, s57, s39
	s_and_b64 s[46:47], s[4:5], exec
	s_cselect_b32 s0, s39, s37
	s_cselect_b32 s29, s38, s36
	s_mov_b64 s[46:47], 0
	s_mov_b32 s31, -2
	s_add_u32 s50, s46, 0x100
	s_addc_u32 s51, s47, 0
	s_add_u32 s3, s46, 0xfffff900
	v_cmp_gt_u64_e32 vcc, s[50:51], v[192:193]
	s_addc_u32 s33, s47, -1
	s_and_b64 s[76:77], vcc, exec
	s_cselect_b32 s50, s3, s50
	s_cselect_b32 s51, s33, s51
	s_add_u32 s3, s92, s50
	s_addc_u32 s33, s93, s51
	s_add_u32 s43, s36, s50
	s_addc_u32 s54, s37, s51
	s_add_i32 s69, 0, 0x10000
	s_cmp_eq_u32 s31, 12
	s_cselect_b32 s97, s7, s33
	s_cselect_b32 s96, s11, s3
	s_cselect_b32 s95, s0, s54
	s_cselect_b32 s94, s29, s43
	s_add_i32 s3, 0, 0x14000
	v_add_u32_e32 v100, s69, v184
	v_add_u32_e32 v168, s3, v184
	ds_read_b128 v[40:43], v100
	ds_read_b128 v[60:63], v100 offset:1024
	ds_read_b128 v[80:83], v100 offset:2048
	ds_read_b128 v[100:103], v100 offset:3072
	ds_read_b128 v[120:123], v168
	ds_read_b128 v[140:143], v168 offset:1024
	ds_read_b128 v[152:155], v168 offset:2048
	ds_read_b128 v[168:171], v168 offset:3072
	s_add_u32 s33, s92, s46
	s_addc_u32 s43, s93, s47
	s_add_u32 s46, s33, 0x40080
	s_addc_u32 s47, s43, 0
	s_add_i32 m0, s23, 0xc000
	ds_read_b128 v[172:175], v202
	ds_read_b128 v[176:179], v202 offset:1024
	ds_read_b128 v[180:183], v202 offset:2048
	ds_read_b128 v[204:207], v202 offset:3072
	ds_read_b128 v[208:211], v202 offset:4096
	ds_read_b128 v[212:215], v202 offset:5120
	ds_read_b128 v[216:219], v202 offset:6144
	ds_read_b128 v[220:223], v202 offset:7168
	global_load_lds_dwordx4 v156, s[46:47]
	s_add_i32 m0, s23, 0xe000
	s_nop 0
	global_load_lds_dwordx4 v160, s[46:47]
	s_waitcnt vmcnt(8)
	s_waitcnt lgkmcnt(0)
	s_barrier
	s_setprio 1
	s_waitcnt lgkmcnt(0)
	v_mfma_f32_16x16x32_bf16 v[148:151], v[40:43], v[172:175], 0
	v_mfma_f32_16x16x32_bf16 v[144:147], v[80:83], v[172:175], 0
	v_mfma_f32_16x16x32_bf16 v[128:131], v[40:43], v[180:183], 0
	v_mfma_f32_16x16x32_bf16 v[124:127], v[80:83], v[180:183], 0
	v_mfma_f32_16x16x32_bf16 v[108:111], v[40:43], v[208:211], 0
	v_mfma_f32_16x16x32_bf16 v[104:107], v[80:83], v[208:211], 0
	v_mfma_f32_16x16x32_bf16 v[88:91], v[40:43], v[216:219], 0
	v_mfma_f32_16x16x32_bf16 v[84:87], v[80:83], v[216:219], 0
	v_mfma_f32_16x16x32_bf16 v[148:151], v[60:63], v[176:179], v[148:151]
	v_mfma_f32_16x16x32_bf16 v[144:147], v[100:103], v[176:179], v[144:147]
	v_mfma_f32_16x16x32_bf16 v[128:131], v[60:63], v[204:207], v[128:131]
	v_mfma_f32_16x16x32_bf16 v[124:127], v[100:103], v[204:207], v[124:127]
	v_mfma_f32_16x16x32_bf16 v[108:111], v[60:63], v[212:215], v[108:111]
	v_mfma_f32_16x16x32_bf16 v[104:107], v[100:103], v[212:215], v[104:107]
	v_mfma_f32_16x16x32_bf16 v[88:91], v[60:63], v[220:223], v[88:91]
	v_mfma_f32_16x16x32_bf16 v[84:87], v[100:103], v[220:223], v[84:87]
	s_setprio 0
	s_setprio 1
	v_mfma_f32_16x16x32_bf16 v[136:139], v[120:123], v[172:175], 0
	v_mfma_f32_16x16x32_bf16 v[132:135], v[152:155], v[172:175], 0
	v_mfma_f32_16x16x32_bf16 v[116:119], v[120:123], v[180:183], 0
	v_mfma_f32_16x16x32_bf16 v[112:115], v[152:155], v[180:183], 0
	v_mfma_f32_16x16x32_bf16 v[96:99], v[120:123], v[208:211], 0
	v_mfma_f32_16x16x32_bf16 v[92:95], v[152:155], v[208:211], 0
	v_mfma_f32_16x16x32_bf16 v[76:79], v[120:123], v[216:219], 0
	v_mfma_f32_16x16x32_bf16 v[72:75], v[152:155], v[216:219], 0
	v_mfma_f32_16x16x32_bf16 v[136:139], v[140:143], v[176:179], v[136:139]
	v_mfma_f32_16x16x32_bf16 v[132:135], v[168:171], v[176:179], v[132:135]
	v_mfma_f32_16x16x32_bf16 v[116:119], v[140:143], v[204:207], v[116:119]
	v_mfma_f32_16x16x32_bf16 v[112:115], v[168:171], v[204:207], v[112:115]
	v_mfma_f32_16x16x32_bf16 v[96:99], v[140:143], v[212:215], v[96:99]
	v_mfma_f32_16x16x32_bf16 v[92:95], v[168:171], v[212:215], v[92:95]
	v_mfma_f32_16x16x32_bf16 v[76:79], v[140:143], v[220:223], v[76:79]
	v_mfma_f32_16x16x32_bf16 v[72:75], v[168:171], v[220:223], v[72:75]
	s_setprio 0
	s_barrier
	s_add_i32 s33, s69, s60
	s_mov_b32 m0, s33
	ds_read_b128 v[172:175], v202 offset:16384
	ds_read_b128 v[176:179], v202 offset:17408
	ds_read_b128 v[180:183], v202 offset:18432
	ds_read_b128 v[204:207], v202 offset:19456
	ds_read_b128 v[208:211], v202 offset:20480
	ds_read_b128 v[212:215], v202 offset:21504
	ds_read_b128 v[216:219], v202 offset:22528
	ds_read_b128 v[220:223], v202 offset:23552
	global_load_lds_dwordx4 v158, s[94:95]
	s_add_i32 m0, s33, 0x2000
	s_add_u32 s46, s94, 0x40000
	s_addc_u32 s47, s95, 0
	s_add_i32 s3, s3, s60
	global_load_lds_dwordx4 v162, s[94:95]
	s_mov_b32 m0, s3
	s_nop 0
	global_load_lds_dwordx4 v158, s[46:47]
	s_add_i32 m0, s3, 0x2000
	s_nop 0
	global_load_lds_dwordx4 v162, s[46:47]
	s_mov_b32 m0, s23
	s_nop 0
	global_load_lds_dwordx4 v156, s[96:97]
	s_mov_b32 m0, s87
	s_nop 0
	global_load_lds_dwordx4 v160, s[96:97]
	s_waitcnt vmcnt(8)
	s_waitcnt lgkmcnt(0)
	s_barrier
	s_setprio 1
	s_waitcnt lgkmcnt(0)
	v_mfma_f32_16x16x32_bf16 v[68:71], v[40:43], v[172:175], 0
	v_mfma_f32_16x16x32_bf16 v[64:67], v[80:83], v[172:175], 0
	v_mfma_f32_16x16x32_bf16 v[48:51], v[40:43], v[180:183], 0
	v_mfma_f32_16x16x32_bf16 v[44:47], v[80:83], v[180:183], 0
	v_mfma_f32_16x16x32_bf16 v[28:31], v[40:43], v[208:211], 0
	v_mfma_f32_16x16x32_bf16 v[24:27], v[80:83], v[208:211], 0
	v_mfma_f32_16x16x32_bf16 v[12:15], v[40:43], v[216:219], 0
	v_mfma_f32_16x16x32_bf16 v[8:11], v[80:83], v[216:219], 0
	v_mfma_f32_16x16x32_bf16 v[68:71], v[60:63], v[176:179], v[68:71]
	v_mfma_f32_16x16x32_bf16 v[64:67], v[100:103], v[176:179], v[64:67]
	v_mfma_f32_16x16x32_bf16 v[48:51], v[60:63], v[204:207], v[48:51]
	v_mfma_f32_16x16x32_bf16 v[44:47], v[100:103], v[204:207], v[44:47]
	v_mfma_f32_16x16x32_bf16 v[28:31], v[60:63], v[212:215], v[28:31]
	v_mfma_f32_16x16x32_bf16 v[24:27], v[100:103], v[212:215], v[24:27]
	v_mfma_f32_16x16x32_bf16 v[12:15], v[60:63], v[220:223], v[12:15]
	v_mfma_f32_16x16x32_bf16 v[8:11], v[100:103], v[220:223], v[8:11]
	s_setprio 0
	s_setprio 1
	v_mfma_f32_16x16x32_bf16 v[52:55], v[152:155], v[172:175], 0
	v_mfma_f32_16x16x32_bf16 v[36:39], v[120:123], v[180:183], 0
	v_mfma_f32_16x16x32_bf16 v[32:35], v[152:155], v[180:183], 0
	v_mfma_f32_16x16x32_bf16 v[20:23], v[120:123], v[208:211], 0
	v_mfma_f32_16x16x32_bf16 v[16:19], v[152:155], v[208:211], 0
	v_mfma_f32_16x16x32_bf16 v[4:7], v[120:123], v[216:219], 0
	v_mfma_f32_16x16x32_bf16 v[0:3], v[152:155], v[216:219], 0
	v_mfma_f32_16x16x32_bf16 v[40:43], v[120:123], v[172:175], 0
	v_mfma_f32_16x16x32_bf16 v[52:55], v[168:171], v[176:179], v[52:55]
	v_mfma_f32_16x16x32_bf16 v[36:39], v[140:143], v[204:207], v[36:39]
	v_mfma_f32_16x16x32_bf16 v[32:35], v[168:171], v[204:207], v[32:35]
	v_mfma_f32_16x16x32_bf16 v[20:23], v[140:143], v[212:215], v[20:23]
	v_mfma_f32_16x16x32_bf16 v[16:19], v[168:171], v[212:215], v[16:19]
	v_mfma_f32_16x16x32_bf16 v[4:7], v[140:143], v[220:223], v[4:7]
	v_mfma_f32_16x16x32_bf16 v[0:3], v[168:171], v[220:223], v[0:3]
	v_mfma_f32_16x16x32_bf16 v[40:43], v[140:143], v[176:179], v[40:43]
	s_setprio 0
	s_barrier
	s_add_i32 s3, 0, 0x18000
	s_add_i32 s33, 0, 0x1c000
	v_add_u32_e32 v100, s3, v184
	v_add_u32_e32 v168, s33, v184
	ds_read_b128 v[56:59], v100
	ds_read_b128 v[60:63], v100 offset:1024
	ds_read_b128 v[80:83], v100 offset:2048
	ds_read_b128 v[100:103], v100 offset:3072
	ds_read_b128 v[120:123], v168
	ds_read_b128 v[140:143], v168 offset:1024
	ds_read_b128 v[152:155], v168 offset:2048
	ds_read_b128 v[168:171], v168 offset:3072
	s_add_u32 s46, s96, 0x40000
	s_addc_u32 s47, s97, 0
	s_mov_b32 m0, s89
	ds_read_b128 v[172:175], v202 offset:32768
	ds_read_b128 v[176:179], v202 offset:33792
	ds_read_b128 v[180:183], v202 offset:34816
	ds_read_b128 v[204:207], v202 offset:35840
	ds_read_b128 v[208:211], v202 offset:36864
	ds_read_b128 v[212:215], v202 offset:37888
	ds_read_b128 v[216:219], v202 offset:38912
	ds_read_b128 v[220:223], v202 offset:39936
	global_load_lds_dwordx4 v156, s[46:47]
	s_mov_b32 m0, s98
	s_nop 0
	global_load_lds_dwordx4 v160, s[46:47]
	s_waitcnt vmcnt(8)
	s_waitcnt lgkmcnt(0)
	s_barrier
	s_setprio 1
	s_waitcnt lgkmcnt(0)
	v_mfma_f32_16x16x32_bf16 v[148:151], v[56:59], v[172:175], v[148:151]
	v_mfma_f32_16x16x32_bf16 v[144:147], v[80:83], v[172:175], v[144:147]
	v_mfma_f32_16x16x32_bf16 v[128:131], v[56:59], v[180:183], v[128:131]
	v_mfma_f32_16x16x32_bf16 v[124:127], v[80:83], v[180:183], v[124:127]
	v_mfma_f32_16x16x32_bf16 v[108:111], v[56:59], v[208:211], v[108:111]
	v_mfma_f32_16x16x32_bf16 v[104:107], v[80:83], v[208:211], v[104:107]
	v_mfma_f32_16x16x32_bf16 v[88:91], v[56:59], v[216:219], v[88:91]
	v_mfma_f32_16x16x32_bf16 v[84:87], v[80:83], v[216:219], v[84:87]
	v_mfma_f32_16x16x32_bf16 v[148:151], v[60:63], v[176:179], v[148:151]
	v_mfma_f32_16x16x32_bf16 v[144:147], v[100:103], v[176:179], v[144:147]
	v_mfma_f32_16x16x32_bf16 v[128:131], v[60:63], v[204:207], v[128:131]
	v_mfma_f32_16x16x32_bf16 v[124:127], v[100:103], v[204:207], v[124:127]
	v_mfma_f32_16x16x32_bf16 v[108:111], v[60:63], v[212:215], v[108:111]
	v_mfma_f32_16x16x32_bf16 v[104:107], v[100:103], v[212:215], v[104:107]
	v_mfma_f32_16x16x32_bf16 v[88:91], v[60:63], v[220:223], v[88:91]
	v_mfma_f32_16x16x32_bf16 v[84:87], v[100:103], v[220:223], v[84:87]
	s_setprio 0
	s_setprio 1
	v_mfma_f32_16x16x32_bf16 v[136:139], v[120:123], v[172:175], v[136:139]
	v_mfma_f32_16x16x32_bf16 v[132:135], v[152:155], v[172:175], v[132:135]
	v_mfma_f32_16x16x32_bf16 v[116:119], v[120:123], v[180:183], v[116:119]
	v_mfma_f32_16x16x32_bf16 v[112:115], v[152:155], v[180:183], v[112:115]
	v_mfma_f32_16x16x32_bf16 v[96:99], v[120:123], v[208:211], v[96:99]
	v_mfma_f32_16x16x32_bf16 v[92:95], v[152:155], v[208:211], v[92:95]
	v_mfma_f32_16x16x32_bf16 v[76:79], v[120:123], v[216:219], v[76:79]
	v_mfma_f32_16x16x32_bf16 v[72:75], v[152:155], v[216:219], v[72:75]
	v_mfma_f32_16x16x32_bf16 v[136:139], v[140:143], v[176:179], v[136:139]
	v_mfma_f32_16x16x32_bf16 v[132:135], v[168:171], v[176:179], v[132:135]
	v_mfma_f32_16x16x32_bf16 v[116:119], v[140:143], v[204:207], v[116:119]
	v_mfma_f32_16x16x32_bf16 v[112:115], v[168:171], v[204:207], v[112:115]
	v_mfma_f32_16x16x32_bf16 v[96:99], v[140:143], v[212:215], v[96:99]
	v_mfma_f32_16x16x32_bf16 v[92:95], v[168:171], v[212:215], v[92:95]
	v_mfma_f32_16x16x32_bf16 v[76:79], v[140:143], v[220:223], v[76:79]
	v_mfma_f32_16x16x32_bf16 v[72:75], v[168:171], v[220:223], v[72:75]
	s_setprio 0
	s_barrier
	s_add_i32 s3, s3, s60
	s_add_u32 s100, s94, 0x80
	s_addc_u32 s101, s95, 0
	s_mov_b32 m0, s3
	ds_read_b128 v[172:175], v202 offset:49152
	ds_read_b128 v[176:179], v202 offset:50176
	ds_read_b128 v[180:183], v202 offset:51200
	ds_read_b128 v[204:207], v202 offset:52224
	ds_read_b128 v[208:211], v202 offset:53248
	ds_read_b128 v[212:215], v202 offset:54272
	ds_read_b128 v[216:219], v202 offset:55296
	ds_read_b128 v[220:223], v202 offset:56320
	global_load_lds_dwordx4 v158, s[100:101]
	s_add_i32 m0, s3, 0x2000
	s_add_u32 s46, s94, 0x40080
	s_addc_u32 s47, s95, 0
	s_add_i32 s3, s33, s60
	global_load_lds_dwordx4 v162, s[100:101]
	s_mov_b32 m0, s3
	s_nop 0
	global_load_lds_dwordx4 v158, s[46:47]
	s_add_i32 m0, s3, 0x2000
	s_nop 0
	global_load_lds_dwordx4 v162, s[46:47]
	s_add_u32 s100, s96, 0x80
	s_addc_u32 s101, s97, 0
	s_mov_b32 m0, s99
	s_nop 0
	global_load_lds_dwordx4 v156, s[100:101]
	s_mov_b32 m0, s16
	s_nop 0
	global_load_lds_dwordx4 v160, s[100:101]
	s_waitcnt vmcnt(8)
	s_waitcnt lgkmcnt(0)
	s_barrier
	s_setprio 1
	s_waitcnt lgkmcnt(0)
	v_mfma_f32_16x16x32_bf16 v[68:71], v[56:59], v[172:175], v[68:71]
	v_mfma_f32_16x16x32_bf16 v[64:67], v[80:83], v[172:175], v[64:67]
	v_mfma_f32_16x16x32_bf16 v[48:51], v[56:59], v[180:183], v[48:51]
	v_mfma_f32_16x16x32_bf16 v[44:47], v[80:83], v[180:183], v[44:47]
	v_mfma_f32_16x16x32_bf16 v[28:31], v[56:59], v[208:211], v[28:31]
	v_mfma_f32_16x16x32_bf16 v[24:27], v[80:83], v[208:211], v[24:27]
	v_mfma_f32_16x16x32_bf16 v[12:15], v[56:59], v[216:219], v[12:15]
	v_mfma_f32_16x16x32_bf16 v[8:11], v[80:83], v[216:219], v[8:11]
	v_mfma_f32_16x16x32_bf16 v[68:71], v[60:63], v[176:179], v[68:71]
	v_mfma_f32_16x16x32_bf16 v[64:67], v[100:103], v[176:179], v[64:67]
	v_mfma_f32_16x16x32_bf16 v[48:51], v[60:63], v[204:207], v[48:51]
	v_mfma_f32_16x16x32_bf16 v[44:47], v[100:103], v[204:207], v[44:47]
	v_mfma_f32_16x16x32_bf16 v[28:31], v[60:63], v[212:215], v[28:31]
	v_mfma_f32_16x16x32_bf16 v[24:27], v[100:103], v[212:215], v[24:27]
	v_mfma_f32_16x16x32_bf16 v[12:15], v[60:63], v[220:223], v[12:15]
	v_mfma_f32_16x16x32_bf16 v[8:11], v[100:103], v[220:223], v[8:11]
	s_setprio 0
	s_setprio 1
	v_mfma_f32_16x16x32_bf16 v[40:43], v[120:123], v[172:175], v[40:43]
	v_mfma_f32_16x16x32_bf16 v[56:59], v[140:143], v[176:179], v[40:43]
	v_mfma_f32_16x16x32_bf16 v[40:43], v[152:155], v[172:175], v[52:55]
	v_mfma_f32_16x16x32_bf16 v[36:39], v[120:123], v[180:183], v[36:39]
	v_mfma_f32_16x16x32_bf16 v[32:35], v[152:155], v[180:183], v[32:35]
	v_mfma_f32_16x16x32_bf16 v[20:23], v[120:123], v[208:211], v[20:23]
	v_mfma_f32_16x16x32_bf16 v[16:19], v[152:155], v[208:211], v[16:19]
	v_mfma_f32_16x16x32_bf16 v[4:7], v[120:123], v[216:219], v[4:7]
	v_mfma_f32_16x16x32_bf16 v[0:3], v[152:155], v[216:219], v[0:3]
	v_mfma_f32_16x16x32_bf16 v[52:55], v[168:171], v[176:179], v[40:43]
	v_mfma_f32_16x16x32_bf16 v[36:39], v[140:143], v[204:207], v[36:39]
	v_mfma_f32_16x16x32_bf16 v[32:35], v[168:171], v[204:207], v[32:35]
	v_mfma_f32_16x16x32_bf16 v[20:23], v[140:143], v[212:215], v[20:23]
	v_mfma_f32_16x16x32_bf16 v[16:19], v[168:171], v[212:215], v[16:19]
	v_mfma_f32_16x16x32_bf16 v[4:7], v[140:143], v[220:223], v[4:7]
	v_mfma_f32_16x16x32_bf16 v[0:3], v[168:171], v[220:223], v[0:3]
	s_setprio 0
	s_barrier
	s_add_i32 s31, s31, 2
	s_cmp_gt_u32 s31, 13
	s_mov_b64 s[46:47], s[50:51]
	s_cbranch_scc1 .Lpeel_exit_mixin
.LBB0_329:
	s_add_u32 s50, s46, 0x100
	s_addc_u32 s51, s47, 0
	s_add_u32 s3, s46, 0xfffff900
	v_cmp_gt_u64_e32 vcc, s[50:51], v[192:193]
	s_addc_u32 s33, s47, -1
	s_and_b64 s[76:77], vcc, exec
	s_cselect_b32 s50, s3, s50
	s_cselect_b32 s51, s33, s51
	s_add_u32 s3, s92, s50
	s_addc_u32 s33, s93, s51
	s_add_u32 s43, s36, s50
	s_addc_u32 s54, s37, s51
	s_add_i32 s69, 0, 0x10000
	s_cmp_eq_u32 s31, 12
	s_cselect_b32 s97, s7, s33
	s_cselect_b32 s96, s11, s3
	s_cselect_b32 s95, s0, s54
	s_cselect_b32 s94, s29, s43
	s_add_i32 s3, 0, 0x14000
	v_add_u32_e32 v100, s69, v184
	v_add_u32_e32 v168, s3, v184
	ds_read_b128 v[40:43], v100
	ds_read_b128 v[60:63], v100 offset:1024
	ds_read_b128 v[80:83], v100 offset:2048
	ds_read_b128 v[100:103], v100 offset:3072
	ds_read_b128 v[120:123], v168
	ds_read_b128 v[140:143], v168 offset:1024
	ds_read_b128 v[152:155], v168 offset:2048
	ds_read_b128 v[168:171], v168 offset:3072
	s_add_u32 s33, s92, s46
	s_addc_u32 s43, s93, s47
	s_add_u32 s46, s33, 0x40080
	s_addc_u32 s47, s43, 0
	s_add_i32 m0, s23, 0xc000
	ds_read_b128 v[172:175], v202
	ds_read_b128 v[176:179], v202 offset:1024
	ds_read_b128 v[180:183], v202 offset:2048
	ds_read_b128 v[204:207], v202 offset:3072
	ds_read_b128 v[208:211], v202 offset:4096
	ds_read_b128 v[212:215], v202 offset:5120
	ds_read_b128 v[216:219], v202 offset:6144
	ds_read_b128 v[220:223], v202 offset:7168
	global_load_lds_dwordx4 v156, s[46:47]
	s_add_i32 m0, s23, 0xe000
	s_nop 0
	global_load_lds_dwordx4 v160, s[46:47]
	s_waitcnt vmcnt(8)
	s_waitcnt lgkmcnt(0)
	s_barrier
	s_setprio 1
	s_waitcnt lgkmcnt(0)
	v_mfma_f32_16x16x32_bf16 v[148:151], v[40:43], v[172:175], v[148:151]
	v_mfma_f32_16x16x32_bf16 v[144:147], v[80:83], v[172:175], v[144:147]
	v_mfma_f32_16x16x32_bf16 v[128:131], v[40:43], v[180:183], v[128:131]
	v_mfma_f32_16x16x32_bf16 v[124:127], v[80:83], v[180:183], v[124:127]
	v_mfma_f32_16x16x32_bf16 v[108:111], v[40:43], v[208:211], v[108:111]
	v_mfma_f32_16x16x32_bf16 v[104:107], v[80:83], v[208:211], v[104:107]
	v_mfma_f32_16x16x32_bf16 v[88:91], v[40:43], v[216:219], v[88:91]
	v_mfma_f32_16x16x32_bf16 v[84:87], v[80:83], v[216:219], v[84:87]
	v_mfma_f32_16x16x32_bf16 v[148:151], v[60:63], v[176:179], v[148:151]
	v_mfma_f32_16x16x32_bf16 v[144:147], v[100:103], v[176:179], v[144:147]
	v_mfma_f32_16x16x32_bf16 v[128:131], v[60:63], v[204:207], v[128:131]
	v_mfma_f32_16x16x32_bf16 v[124:127], v[100:103], v[204:207], v[124:127]
	v_mfma_f32_16x16x32_bf16 v[108:111], v[60:63], v[212:215], v[108:111]
	v_mfma_f32_16x16x32_bf16 v[104:107], v[100:103], v[212:215], v[104:107]
	v_mfma_f32_16x16x32_bf16 v[88:91], v[60:63], v[220:223], v[88:91]
	v_mfma_f32_16x16x32_bf16 v[84:87], v[100:103], v[220:223], v[84:87]
	s_setprio 0
	s_setprio 1
	v_mfma_f32_16x16x32_bf16 v[136:139], v[120:123], v[172:175], v[136:139]
	v_mfma_f32_16x16x32_bf16 v[132:135], v[152:155], v[172:175], v[132:135]
	v_mfma_f32_16x16x32_bf16 v[116:119], v[120:123], v[180:183], v[116:119]
	v_mfma_f32_16x16x32_bf16 v[112:115], v[152:155], v[180:183], v[112:115]
	v_mfma_f32_16x16x32_bf16 v[96:99], v[120:123], v[208:211], v[96:99]
	v_mfma_f32_16x16x32_bf16 v[92:95], v[152:155], v[208:211], v[92:95]
	v_mfma_f32_16x16x32_bf16 v[76:79], v[120:123], v[216:219], v[76:79]
	v_mfma_f32_16x16x32_bf16 v[72:75], v[152:155], v[216:219], v[72:75]
	v_mfma_f32_16x16x32_bf16 v[136:139], v[140:143], v[176:179], v[136:139]
	v_mfma_f32_16x16x32_bf16 v[132:135], v[168:171], v[176:179], v[132:135]
	v_mfma_f32_16x16x32_bf16 v[116:119], v[140:143], v[204:207], v[116:119]
	v_mfma_f32_16x16x32_bf16 v[112:115], v[168:171], v[204:207], v[112:115]
	v_mfma_f32_16x16x32_bf16 v[96:99], v[140:143], v[212:215], v[96:99]
	v_mfma_f32_16x16x32_bf16 v[92:95], v[168:171], v[212:215], v[92:95]
	v_mfma_f32_16x16x32_bf16 v[76:79], v[140:143], v[220:223], v[76:79]
	v_mfma_f32_16x16x32_bf16 v[72:75], v[168:171], v[220:223], v[72:75]
	s_setprio 0
	s_barrier
	s_add_i32 s33, s69, s60
	s_mov_b32 m0, s33
	ds_read_b128 v[172:175], v202 offset:16384
	ds_read_b128 v[176:179], v202 offset:17408
	ds_read_b128 v[180:183], v202 offset:18432
	ds_read_b128 v[204:207], v202 offset:19456
	ds_read_b128 v[208:211], v202 offset:20480
	ds_read_b128 v[212:215], v202 offset:21504
	ds_read_b128 v[216:219], v202 offset:22528
	ds_read_b128 v[220:223], v202 offset:23552
	global_load_lds_dwordx4 v158, s[94:95]
	s_add_i32 m0, s33, 0x2000
	s_add_u32 s46, s94, 0x40000
	s_addc_u32 s47, s95, 0
	s_add_i32 s3, s3, s60
	global_load_lds_dwordx4 v162, s[94:95]
	s_mov_b32 m0, s3
	s_nop 0
	global_load_lds_dwordx4 v158, s[46:47]
	s_add_i32 m0, s3, 0x2000
	s_nop 0
	global_load_lds_dwordx4 v162, s[46:47]
	s_mov_b32 m0, s23
	s_nop 0
	global_load_lds_dwordx4 v156, s[96:97]
	s_mov_b32 m0, s87
	s_nop 0
	global_load_lds_dwordx4 v160, s[96:97]
	s_waitcnt vmcnt(8)
	s_waitcnt lgkmcnt(0)
	s_barrier
	s_setprio 1
	s_waitcnt lgkmcnt(0)
	v_mfma_f32_16x16x32_bf16 v[68:71], v[40:43], v[172:175], v[68:71]
	v_mfma_f32_16x16x32_bf16 v[64:67], v[80:83], v[172:175], v[64:67]
	v_mfma_f32_16x16x32_bf16 v[48:51], v[40:43], v[180:183], v[48:51]
	v_mfma_f32_16x16x32_bf16 v[44:47], v[80:83], v[180:183], v[44:47]
	v_mfma_f32_16x16x32_bf16 v[28:31], v[40:43], v[208:211], v[28:31]
	v_mfma_f32_16x16x32_bf16 v[24:27], v[80:83], v[208:211], v[24:27]
	v_mfma_f32_16x16x32_bf16 v[12:15], v[40:43], v[216:219], v[12:15]
	v_mfma_f32_16x16x32_bf16 v[8:11], v[80:83], v[216:219], v[8:11]
	v_mfma_f32_16x16x32_bf16 v[68:71], v[60:63], v[176:179], v[68:71]
	v_mfma_f32_16x16x32_bf16 v[64:67], v[100:103], v[176:179], v[64:67]
	v_mfma_f32_16x16x32_bf16 v[48:51], v[60:63], v[204:207], v[48:51]
	v_mfma_f32_16x16x32_bf16 v[44:47], v[100:103], v[204:207], v[44:47]
	v_mfma_f32_16x16x32_bf16 v[28:31], v[60:63], v[212:215], v[28:31]
	v_mfma_f32_16x16x32_bf16 v[24:27], v[100:103], v[212:215], v[24:27]
	v_mfma_f32_16x16x32_bf16 v[12:15], v[60:63], v[220:223], v[12:15]
	v_mfma_f32_16x16x32_bf16 v[8:11], v[100:103], v[220:223], v[8:11]
	s_setprio 0
	s_setprio 1
	v_mfma_f32_16x16x32_bf16 v[52:55], v[152:155], v[172:175], v[52:55]
	v_mfma_f32_16x16x32_bf16 v[36:39], v[120:123], v[180:183], v[36:39]
	v_mfma_f32_16x16x32_bf16 v[32:35], v[152:155], v[180:183], v[32:35]
	v_mfma_f32_16x16x32_bf16 v[20:23], v[120:123], v[208:211], v[20:23]
	v_mfma_f32_16x16x32_bf16 v[16:19], v[152:155], v[208:211], v[16:19]
	v_mfma_f32_16x16x32_bf16 v[4:7], v[120:123], v[216:219], v[4:7]
	v_mfma_f32_16x16x32_bf16 v[0:3], v[152:155], v[216:219], v[0:3]
	v_mfma_f32_16x16x32_bf16 v[40:43], v[120:123], v[172:175], v[56:59]
	v_mfma_f32_16x16x32_bf16 v[52:55], v[168:171], v[176:179], v[52:55]
	v_mfma_f32_16x16x32_bf16 v[36:39], v[140:143], v[204:207], v[36:39]
	v_mfma_f32_16x16x32_bf16 v[32:35], v[168:171], v[204:207], v[32:35]
	v_mfma_f32_16x16x32_bf16 v[20:23], v[140:143], v[212:215], v[20:23]
	v_mfma_f32_16x16x32_bf16 v[16:19], v[168:171], v[212:215], v[16:19]
	v_mfma_f32_16x16x32_bf16 v[4:7], v[140:143], v[220:223], v[4:7]
	v_mfma_f32_16x16x32_bf16 v[0:3], v[168:171], v[220:223], v[0:3]
	v_mfma_f32_16x16x32_bf16 v[40:43], v[140:143], v[176:179], v[40:43]
	s_setprio 0
	s_barrier
	s_add_i32 s3, 0, 0x18000
	s_add_i32 s33, 0, 0x1c000
	v_add_u32_e32 v100, s3, v184
	v_add_u32_e32 v168, s33, v184
	ds_read_b128 v[56:59], v100
	ds_read_b128 v[60:63], v100 offset:1024
	ds_read_b128 v[80:83], v100 offset:2048
	ds_read_b128 v[100:103], v100 offset:3072
	ds_read_b128 v[120:123], v168
	ds_read_b128 v[140:143], v168 offset:1024
	ds_read_b128 v[152:155], v168 offset:2048
	ds_read_b128 v[168:171], v168 offset:3072
	s_add_u32 s46, s96, 0x40000
	s_addc_u32 s47, s97, 0
	s_mov_b32 m0, s89
	ds_read_b128 v[172:175], v202 offset:32768
	ds_read_b128 v[176:179], v202 offset:33792
	ds_read_b128 v[180:183], v202 offset:34816
	ds_read_b128 v[204:207], v202 offset:35840
	ds_read_b128 v[208:211], v202 offset:36864
	ds_read_b128 v[212:215], v202 offset:37888
	ds_read_b128 v[216:219], v202 offset:38912
	ds_read_b128 v[220:223], v202 offset:39936
	global_load_lds_dwordx4 v156, s[46:47]
	s_mov_b32 m0, s98
	s_nop 0
	global_load_lds_dwordx4 v160, s[46:47]
	s_waitcnt vmcnt(8)
	s_waitcnt lgkmcnt(0)
	s_barrier
	s_setprio 1
	s_waitcnt lgkmcnt(0)
	v_mfma_f32_16x16x32_bf16 v[148:151], v[56:59], v[172:175], v[148:151]
	v_mfma_f32_16x16x32_bf16 v[144:147], v[80:83], v[172:175], v[144:147]
	v_mfma_f32_16x16x32_bf16 v[128:131], v[56:59], v[180:183], v[128:131]
	v_mfma_f32_16x16x32_bf16 v[124:127], v[80:83], v[180:183], v[124:127]
	v_mfma_f32_16x16x32_bf16 v[108:111], v[56:59], v[208:211], v[108:111]
	v_mfma_f32_16x16x32_bf16 v[104:107], v[80:83], v[208:211], v[104:107]
	v_mfma_f32_16x16x32_bf16 v[88:91], v[56:59], v[216:219], v[88:91]
	v_mfma_f32_16x16x32_bf16 v[84:87], v[80:83], v[216:219], v[84:87]
	v_mfma_f32_16x16x32_bf16 v[148:151], v[60:63], v[176:179], v[148:151]
	v_mfma_f32_16x16x32_bf16 v[144:147], v[100:103], v[176:179], v[144:147]
	v_mfma_f32_16x16x32_bf16 v[128:131], v[60:63], v[204:207], v[128:131]
	v_mfma_f32_16x16x32_bf16 v[124:127], v[100:103], v[204:207], v[124:127]
	v_mfma_f32_16x16x32_bf16 v[108:111], v[60:63], v[212:215], v[108:111]
	v_mfma_f32_16x16x32_bf16 v[104:107], v[100:103], v[212:215], v[104:107]
	v_mfma_f32_16x16x32_bf16 v[88:91], v[60:63], v[220:223], v[88:91]
	v_mfma_f32_16x16x32_bf16 v[84:87], v[100:103], v[220:223], v[84:87]
	s_setprio 0
	s_setprio 1
	v_mfma_f32_16x16x32_bf16 v[136:139], v[120:123], v[172:175], v[136:139]
	v_mfma_f32_16x16x32_bf16 v[132:135], v[152:155], v[172:175], v[132:135]
	v_mfma_f32_16x16x32_bf16 v[116:119], v[120:123], v[180:183], v[116:119]
	v_mfma_f32_16x16x32_bf16 v[112:115], v[152:155], v[180:183], v[112:115]
	v_mfma_f32_16x16x32_bf16 v[96:99], v[120:123], v[208:211], v[96:99]
	v_mfma_f32_16x16x32_bf16 v[92:95], v[152:155], v[208:211], v[92:95]
	v_mfma_f32_16x16x32_bf16 v[76:79], v[120:123], v[216:219], v[76:79]
	v_mfma_f32_16x16x32_bf16 v[72:75], v[152:155], v[216:219], v[72:75]
	v_mfma_f32_16x16x32_bf16 v[136:139], v[140:143], v[176:179], v[136:139]
	v_mfma_f32_16x16x32_bf16 v[132:135], v[168:171], v[176:179], v[132:135]
	v_mfma_f32_16x16x32_bf16 v[116:119], v[140:143], v[204:207], v[116:119]
	v_mfma_f32_16x16x32_bf16 v[112:115], v[168:171], v[204:207], v[112:115]
	v_mfma_f32_16x16x32_bf16 v[96:99], v[140:143], v[212:215], v[96:99]
	v_mfma_f32_16x16x32_bf16 v[92:95], v[168:171], v[212:215], v[92:95]
	v_mfma_f32_16x16x32_bf16 v[76:79], v[140:143], v[220:223], v[76:79]
	v_mfma_f32_16x16x32_bf16 v[72:75], v[168:171], v[220:223], v[72:75]
	s_setprio 0
	s_barrier
	s_add_i32 s3, s3, s60
	s_add_u32 s100, s94, 0x80
	s_addc_u32 s101, s95, 0
	s_mov_b32 m0, s3
	ds_read_b128 v[172:175], v202 offset:49152
	ds_read_b128 v[176:179], v202 offset:50176
	ds_read_b128 v[180:183], v202 offset:51200
	ds_read_b128 v[204:207], v202 offset:52224
	ds_read_b128 v[208:211], v202 offset:53248
	ds_read_b128 v[212:215], v202 offset:54272
	ds_read_b128 v[216:219], v202 offset:55296
	ds_read_b128 v[220:223], v202 offset:56320
	global_load_lds_dwordx4 v158, s[100:101]
	s_add_i32 m0, s3, 0x2000
	s_add_u32 s46, s94, 0x40080
	s_addc_u32 s47, s95, 0
	s_add_i32 s3, s33, s60
	global_load_lds_dwordx4 v162, s[100:101]
	s_mov_b32 m0, s3
	s_nop 0
	global_load_lds_dwordx4 v158, s[46:47]
	s_add_i32 m0, s3, 0x2000
	s_nop 0
	global_load_lds_dwordx4 v162, s[46:47]
	s_add_u32 s100, s96, 0x80
	s_addc_u32 s101, s97, 0
	s_mov_b32 m0, s99
	s_nop 0
	global_load_lds_dwordx4 v156, s[100:101]
	s_mov_b32 m0, s16
	s_nop 0
	global_load_lds_dwordx4 v160, s[100:101]
	s_waitcnt vmcnt(8)
	s_waitcnt lgkmcnt(0)
	s_barrier
	s_setprio 1
	s_waitcnt lgkmcnt(0)
	v_mfma_f32_16x16x32_bf16 v[68:71], v[56:59], v[172:175], v[68:71]
	v_mfma_f32_16x16x32_bf16 v[64:67], v[80:83], v[172:175], v[64:67]
	v_mfma_f32_16x16x32_bf16 v[48:51], v[56:59], v[180:183], v[48:51]
	v_mfma_f32_16x16x32_bf16 v[44:47], v[80:83], v[180:183], v[44:47]
	v_mfma_f32_16x16x32_bf16 v[28:31], v[56:59], v[208:211], v[28:31]
	v_mfma_f32_16x16x32_bf16 v[24:27], v[80:83], v[208:211], v[24:27]
	v_mfma_f32_16x16x32_bf16 v[12:15], v[56:59], v[216:219], v[12:15]
	v_mfma_f32_16x16x32_bf16 v[8:11], v[80:83], v[216:219], v[8:11]
	v_mfma_f32_16x16x32_bf16 v[68:71], v[60:63], v[176:179], v[68:71]
	v_mfma_f32_16x16x32_bf16 v[64:67], v[100:103], v[176:179], v[64:67]
	v_mfma_f32_16x16x32_bf16 v[48:51], v[60:63], v[204:207], v[48:51]
	v_mfma_f32_16x16x32_bf16 v[44:47], v[100:103], v[204:207], v[44:47]
	v_mfma_f32_16x16x32_bf16 v[28:31], v[60:63], v[212:215], v[28:31]
	v_mfma_f32_16x16x32_bf16 v[24:27], v[100:103], v[212:215], v[24:27]
	v_mfma_f32_16x16x32_bf16 v[12:15], v[60:63], v[220:223], v[12:15]
	v_mfma_f32_16x16x32_bf16 v[8:11], v[100:103], v[220:223], v[8:11]
	s_setprio 0
	s_setprio 1
	v_mfma_f32_16x16x32_bf16 v[40:43], v[120:123], v[172:175], v[40:43]
	v_mfma_f32_16x16x32_bf16 v[56:59], v[140:143], v[176:179], v[40:43]
	v_mfma_f32_16x16x32_bf16 v[40:43], v[152:155], v[172:175], v[52:55]
	v_mfma_f32_16x16x32_bf16 v[36:39], v[120:123], v[180:183], v[36:39]
	v_mfma_f32_16x16x32_bf16 v[32:35], v[152:155], v[180:183], v[32:35]
	v_mfma_f32_16x16x32_bf16 v[20:23], v[120:123], v[208:211], v[20:23]
	v_mfma_f32_16x16x32_bf16 v[16:19], v[152:155], v[208:211], v[16:19]
	v_mfma_f32_16x16x32_bf16 v[4:7], v[120:123], v[216:219], v[4:7]
	v_mfma_f32_16x16x32_bf16 v[0:3], v[152:155], v[216:219], v[0:3]
	v_mfma_f32_16x16x32_bf16 v[52:55], v[168:171], v[176:179], v[40:43]
	v_mfma_f32_16x16x32_bf16 v[36:39], v[140:143], v[204:207], v[36:39]
	v_mfma_f32_16x16x32_bf16 v[32:35], v[168:171], v[204:207], v[32:35]
	v_mfma_f32_16x16x32_bf16 v[20:23], v[140:143], v[212:215], v[20:23]
	v_mfma_f32_16x16x32_bf16 v[16:19], v[168:171], v[212:215], v[16:19]
	v_mfma_f32_16x16x32_bf16 v[4:7], v[140:143], v[220:223], v[4:7]
	v_mfma_f32_16x16x32_bf16 v[0:3], v[168:171], v[220:223], v[0:3]
	s_setprio 0
	s_barrier
	s_add_i32 s31, s31, 2
	s_cmp_gt_u32 s31, 13
	s_mov_b64 s[46:47], s[50:51]
	s_cbranch_scc0 .LBB0_329

.LBB0_489:
	s_add_u32 s0, s34, s92
	s_addc_u32 s43, s35, 0
	s_mov_b64 s[36:37], 0
	s_mov_b32 s86, 0
	s_add_u32 s38, s36, 0x100
	s_addc_u32 s39, s37, 0
	v_mov_b64_e32 v[120:121], s[24:25]
	v_cmp_ge_u64_e32 vcc, s[38:39], v[120:121]
	s_and_b64 s[46:47], vcc, exec
	s_cselect_b32 s47, s24, 0
	s_cselect_b32 s46, 0, 0
	s_sub_u32 s38, s38, s47
	s_subb_u32 s39, s39, s46
	s_sub_u32 s47, s36, s47
	s_subb_u32 s46, s37, s46
	s_add_u32 vcc_lo, s34, s47
	s_addc_u32 vcc_hi, s35, s46
	s_add_u32 vcc_lo, vcc_lo, 0x100
	s_addc_u32 vcc_hi, vcc_hi, 0
	s_add_u32 s47, s30, s47
	s_addc_u32 s46, s31, s46
	s_add_u32 s69, s47, 0x100
	s_addc_u32 s3, s46, 0
	s_add_i32 s33, 0, 0x10000
	s_cmp_eq_u32 s99, s86
	s_cselect_b32 s47, s11, vcc_hi
	s_cselect_b32 s46, s10, vcc_lo
	s_cselect_b32 vcc_hi, s29, s3
	s_cselect_b32 vcc_lo, s28, s69
	s_add_i32 s3, 0, 0x14000
	v_add_u32_e32 v132, s33, v234
	v_add_u32_e32 v148, s3, v234
	ds_read_b128 v[120:123], v132
	ds_read_b128 v[124:127], v132 offset:1024
	ds_read_b128 v[128:131], v132 offset:2048
	ds_read_b128 v[132:135], v132 offset:3072
	ds_read_b128 v[136:139], v148
	ds_read_b128 v[140:143], v148 offset:1024
	ds_read_b128 v[144:147], v148 offset:2048
	ds_read_b128 v[148:151], v148 offset:3072
	s_add_u32 s36, s0, s36
	s_addc_u32 s37, s43, s37
	s_add_u32 s100, s36, 0x80
	s_addc_u32 s101, s37, 0
	s_add_i32 m0, s94, 0xc000
	ds_read_b128 v[152:155], v248
	ds_read_b128 v[156:159], v248 offset:1024
	ds_read_b128 v[160:163], v248 offset:2048
	ds_read_b128 v[172:175], v248 offset:3072
	ds_read_b128 v[176:179], v248 offset:4096
	ds_read_b128 v[180:183], v248 offset:5120
	ds_read_b128 v[184:187], v248 offset:6144
	ds_read_b128 v[208:211], v248 offset:7168
	global_load_lds_dwordx4 v202, s[100:101]
	s_add_i32 m0, s94, 0xe000
	s_nop 0
	global_load_lds_dwordx4 v204, s[100:101]
	s_waitcnt vmcnt(8)
	s_waitcnt lgkmcnt(0)
	s_barrier
	s_setprio 1
	s_waitcnt lgkmcnt(0)
	v_mfma_f32_16x16x32_bf16 v[168:171], v[120:123], v[152:155], 0
	v_mfma_f32_16x16x32_bf16 v[164:167], v[128:131], v[152:155], 0
	v_mfma_f32_16x16x32_bf16 v[108:111], v[120:123], v[160:163], 0
	v_mfma_f32_16x16x32_bf16 v[104:107], v[128:131], v[160:163], 0
	v_mfma_f32_16x16x32_bf16 v[92:95], v[120:123], v[176:179], 0
	v_mfma_f32_16x16x32_bf16 v[88:91], v[128:131], v[176:179], 0
	v_mfma_f32_16x16x32_bf16 v[76:79], v[120:123], v[184:187], 0
	v_mfma_f32_16x16x32_bf16 v[72:75], v[128:131], v[184:187], 0
	v_mfma_f32_16x16x32_bf16 v[168:171], v[124:127], v[156:159], v[168:171]
	v_mfma_f32_16x16x32_bf16 v[164:167], v[132:135], v[156:159], v[164:167]
	v_mfma_f32_16x16x32_bf16 v[108:111], v[124:127], v[172:175], v[108:111]
	v_mfma_f32_16x16x32_bf16 v[104:107], v[132:135], v[172:175], v[104:107]
	v_mfma_f32_16x16x32_bf16 v[92:95], v[124:127], v[180:183], v[92:95]
	v_mfma_f32_16x16x32_bf16 v[88:91], v[132:135], v[180:183], v[88:91]
	v_mfma_f32_16x16x32_bf16 v[76:79], v[124:127], v[208:211], v[76:79]
	v_mfma_f32_16x16x32_bf16 v[72:75], v[132:135], v[208:211], v[72:75]
	s_setprio 0
	s_setprio 1
	v_mfma_f32_16x16x32_bf16 v[116:119], v[136:139], v[152:155], 0
	v_mfma_f32_16x16x32_bf16 v[112:115], v[144:147], v[152:155], 0
	v_mfma_f32_16x16x32_bf16 v[100:103], v[136:139], v[160:163], 0
	v_mfma_f32_16x16x32_bf16 v[96:99], v[144:147], v[160:163], 0
	v_mfma_f32_16x16x32_bf16 v[84:87], v[136:139], v[176:179], 0
	v_mfma_f32_16x16x32_bf16 v[80:83], v[144:147], v[176:179], 0
	v_mfma_f32_16x16x32_bf16 v[68:71], v[136:139], v[184:187], 0
	v_mfma_f32_16x16x32_bf16 v[64:67], v[144:147], v[184:187], 0
	v_mfma_f32_16x16x32_bf16 v[116:119], v[140:143], v[156:159], v[116:119]
	v_mfma_f32_16x16x32_bf16 v[112:115], v[148:151], v[156:159], v[112:115]
	v_mfma_f32_16x16x32_bf16 v[100:103], v[140:143], v[172:175], v[100:103]
	v_mfma_f32_16x16x32_bf16 v[96:99], v[148:151], v[172:175], v[96:99]
	v_mfma_f32_16x16x32_bf16 v[84:87], v[140:143], v[180:183], v[84:87]
	v_mfma_f32_16x16x32_bf16 v[80:83], v[148:151], v[180:183], v[80:83]
	v_mfma_f32_16x16x32_bf16 v[68:71], v[140:143], v[208:211], v[68:71]
	v_mfma_f32_16x16x32_bf16 v[64:67], v[148:151], v[208:211], v[64:67]
	s_setprio 0
	s_barrier
	s_add_i32 s33, s33, s89
	s_mov_b64 s[100:101], vcc
	s_mov_b32 m0, s33
	ds_read_b128 v[152:155], v248 offset:16384
	ds_read_b128 v[156:159], v248 offset:17408
	ds_read_b128 v[160:163], v248 offset:18432
	ds_read_b128 v[172:175], v248 offset:19456
	ds_read_b128 v[176:179], v248 offset:20480
	ds_read_b128 v[180:183], v248 offset:21504
	ds_read_b128 v[184:187], v248 offset:22528
	ds_read_b128 v[208:211], v248 offset:23552
	global_load_lds_dwordx4 v188, s[100:101]
	s_add_i32 m0, s33, 0x2000
	s_add_u32 s36, vcc_lo, s92
	s_addc_u32 s37, vcc_hi, 0
	s_add_i32 s3, s3, s89
	global_load_lds_dwordx4 v206, s[100:101]
	s_mov_b32 m0, s3
	s_nop 0
	global_load_lds_dwordx4 v188, s[36:37]
	s_add_i32 m0, s3, 0x2000
	s_nop 0
	global_load_lds_dwordx4 v206, s[36:37]
	s_mov_b32 m0, s94
	s_nop 0
	global_load_lds_dwordx4 v202, s[46:47]
	s_mov_b32 m0, s95
	s_nop 0
	global_load_lds_dwordx4 v204, s[46:47]
	s_waitcnt vmcnt(8)
	s_waitcnt lgkmcnt(0)
	s_barrier
	s_setprio 1
	s_waitcnt lgkmcnt(0)
	v_mfma_f32_16x16x32_bf16 v[60:63], v[120:123], v[152:155], 0
	v_mfma_f32_16x16x32_bf16 v[56:59], v[128:131], v[152:155], 0
	v_mfma_f32_16x16x32_bf16 v[44:47], v[120:123], v[160:163], 0
	v_mfma_f32_16x16x32_bf16 v[40:43], v[128:131], v[160:163], 0
	v_mfma_f32_16x16x32_bf16 v[28:31], v[120:123], v[176:179], 0
	v_mfma_f32_16x16x32_bf16 v[24:27], v[128:131], v[176:179], 0
	v_mfma_f32_16x16x32_bf16 v[12:15], v[120:123], v[184:187], 0
	v_mfma_f32_16x16x32_bf16 v[8:11], v[128:131], v[184:187], 0
	v_mfma_f32_16x16x32_bf16 v[60:63], v[124:127], v[156:159], v[60:63]
	v_mfma_f32_16x16x32_bf16 v[56:59], v[132:135], v[156:159], v[56:59]
	v_mfma_f32_16x16x32_bf16 v[44:47], v[124:127], v[172:175], v[44:47]
	v_mfma_f32_16x16x32_bf16 v[40:43], v[132:135], v[172:175], v[40:43]
	v_mfma_f32_16x16x32_bf16 v[28:31], v[124:127], v[180:183], v[28:31]
	v_mfma_f32_16x16x32_bf16 v[24:27], v[132:135], v[180:183], v[24:27]
	v_mfma_f32_16x16x32_bf16 v[12:15], v[124:127], v[208:211], v[12:15]
	v_mfma_f32_16x16x32_bf16 v[8:11], v[132:135], v[208:211], v[8:11]
	s_setprio 0
	s_setprio 1
	v_mfma_f32_16x16x32_bf16 v[52:55], v[136:139], v[152:155], 0
	v_mfma_f32_16x16x32_bf16 v[48:51], v[144:147], v[152:155], 0
	v_mfma_f32_16x16x32_bf16 v[36:39], v[136:139], v[160:163], 0
	v_mfma_f32_16x16x32_bf16 v[32:35], v[144:147], v[160:163], 0
	v_mfma_f32_16x16x32_bf16 v[20:23], v[136:139], v[176:179], 0
	v_mfma_f32_16x16x32_bf16 v[16:19], v[144:147], v[176:179], 0
	v_mfma_f32_16x16x32_bf16 v[4:7], v[136:139], v[184:187], 0
	v_mfma_f32_16x16x32_bf16 v[0:3], v[144:147], v[184:187], 0
	v_mfma_f32_16x16x32_bf16 v[52:55], v[140:143], v[156:159], v[52:55]
	v_mfma_f32_16x16x32_bf16 v[48:51], v[148:151], v[156:159], v[48:51]
	v_mfma_f32_16x16x32_bf16 v[36:39], v[140:143], v[172:175], v[36:39]
	v_mfma_f32_16x16x32_bf16 v[32:35], v[148:151], v[172:175], v[32:35]
	v_mfma_f32_16x16x32_bf16 v[20:23], v[140:143], v[180:183], v[20:23]
	v_mfma_f32_16x16x32_bf16 v[16:19], v[148:151], v[180:183], v[16:19]
	v_mfma_f32_16x16x32_bf16 v[4:7], v[140:143], v[208:211], v[4:7]
	v_mfma_f32_16x16x32_bf16 v[0:3], v[148:151], v[208:211], v[0:3]
	s_setprio 0
	s_barrier
	s_add_i32 s3, 0, 0x18000
	s_add_i32 s33, 0, 0x1c000
	v_add_u32_e32 v132, s3, v234
	v_add_u32_e32 v148, s33, v234
	ds_read_b128 v[120:123], v132
	ds_read_b128 v[124:127], v132 offset:1024
	ds_read_b128 v[128:131], v132 offset:2048
	ds_read_b128 v[132:135], v132 offset:3072
	ds_read_b128 v[136:139], v148
	ds_read_b128 v[140:143], v148 offset:1024
	ds_read_b128 v[144:147], v148 offset:2048
	ds_read_b128 v[148:151], v148 offset:3072
	s_add_u32 s36, s46, s92
	s_addc_u32 s37, s47, 0
	s_mov_b32 m0, s96
	ds_read_b128 v[152:155], v248 offset:32768
	ds_read_b128 v[156:159], v248 offset:33792
	ds_read_b128 v[160:163], v248 offset:34816
	ds_read_b128 v[172:175], v248 offset:35840
	ds_read_b128 v[176:179], v248 offset:36864
	ds_read_b128 v[180:183], v248 offset:37888
	ds_read_b128 v[184:187], v248 offset:38912
	ds_read_b128 v[208:211], v248 offset:39936
	global_load_lds_dwordx4 v202, s[36:37]
	s_mov_b32 m0, s97
	s_nop 0
	global_load_lds_dwordx4 v204, s[36:37]
	s_waitcnt vmcnt(8)
	s_waitcnt lgkmcnt(0)
	s_barrier
	s_setprio 1
	s_waitcnt lgkmcnt(0)
	v_mfma_f32_16x16x32_bf16 v[168:171], v[120:123], v[152:155], v[168:171]
	v_mfma_f32_16x16x32_bf16 v[164:167], v[128:131], v[152:155], v[164:167]
	v_mfma_f32_16x16x32_bf16 v[108:111], v[120:123], v[160:163], v[108:111]
	v_mfma_f32_16x16x32_bf16 v[104:107], v[128:131], v[160:163], v[104:107]
	v_mfma_f32_16x16x32_bf16 v[92:95], v[120:123], v[176:179], v[92:95]
	v_mfma_f32_16x16x32_bf16 v[88:91], v[128:131], v[176:179], v[88:91]
	v_mfma_f32_16x16x32_bf16 v[76:79], v[120:123], v[184:187], v[76:79]
	v_mfma_f32_16x16x32_bf16 v[72:75], v[128:131], v[184:187], v[72:75]
	v_mfma_f32_16x16x32_bf16 v[168:171], v[124:127], v[156:159], v[168:171]
	v_mfma_f32_16x16x32_bf16 v[164:167], v[132:135], v[156:159], v[164:167]
	v_mfma_f32_16x16x32_bf16 v[108:111], v[124:127], v[172:175], v[108:111]
	v_mfma_f32_16x16x32_bf16 v[104:107], v[132:135], v[172:175], v[104:107]
	v_mfma_f32_16x16x32_bf16 v[92:95], v[124:127], v[180:183], v[92:95]
	v_mfma_f32_16x16x32_bf16 v[88:91], v[132:135], v[180:183], v[88:91]
	v_mfma_f32_16x16x32_bf16 v[76:79], v[124:127], v[208:211], v[76:79]
	v_mfma_f32_16x16x32_bf16 v[72:75], v[132:135], v[208:211], v[72:75]
	s_setprio 0
	s_setprio 1
	v_mfma_f32_16x16x32_bf16 v[116:119], v[136:139], v[152:155], v[116:119]
	v_mfma_f32_16x16x32_bf16 v[112:115], v[144:147], v[152:155], v[112:115]
	v_mfma_f32_16x16x32_bf16 v[100:103], v[136:139], v[160:163], v[100:103]
	v_mfma_f32_16x16x32_bf16 v[96:99], v[144:147], v[160:163], v[96:99]
	v_mfma_f32_16x16x32_bf16 v[84:87], v[136:139], v[176:179], v[84:87]
	v_mfma_f32_16x16x32_bf16 v[80:83], v[144:147], v[176:179], v[80:83]
	v_mfma_f32_16x16x32_bf16 v[68:71], v[136:139], v[184:187], v[68:71]
	v_mfma_f32_16x16x32_bf16 v[64:67], v[144:147], v[184:187], v[64:67]
	v_mfma_f32_16x16x32_bf16 v[116:119], v[140:143], v[156:159], v[116:119]
	v_mfma_f32_16x16x32_bf16 v[112:115], v[148:151], v[156:159], v[112:115]
	v_mfma_f32_16x16x32_bf16 v[100:103], v[140:143], v[172:175], v[100:103]
	v_mfma_f32_16x16x32_bf16 v[96:99], v[148:151], v[172:175], v[96:99]
	v_mfma_f32_16x16x32_bf16 v[84:87], v[140:143], v[180:183], v[84:87]
	v_mfma_f32_16x16x32_bf16 v[80:83], v[148:151], v[180:183], v[80:83]
	v_mfma_f32_16x16x32_bf16 v[68:71], v[140:143], v[208:211], v[68:71]
	v_mfma_f32_16x16x32_bf16 v[64:67], v[148:151], v[208:211], v[64:67]
	s_setprio 0
	s_barrier
	s_add_i32 s3, s3, s89
	s_add_u32 s100, vcc_lo, 0x80
	s_addc_u32 s101, vcc_hi, 0
	s_mov_b32 m0, s3
	ds_read_b128 v[152:155], v248 offset:49152
	ds_read_b128 v[156:159], v248 offset:50176
	ds_read_b128 v[160:163], v248 offset:51200
	ds_read_b128 v[172:175], v248 offset:52224
	ds_read_b128 v[176:179], v248 offset:53248
	ds_read_b128 v[180:183], v248 offset:54272
	ds_read_b128 v[184:187], v248 offset:55296
	ds_read_b128 v[208:211], v248 offset:56320
	global_load_lds_dwordx4 v188, s[100:101]
	s_add_i32 m0, s3, 0x2000
	s_add_i32 s3, s33, s89
	global_load_lds_dwordx4 v206, s[100:101]
	s_add_u32 s36, s100, s92
	s_addc_u32 s37, s101, 0
	s_mov_b32 m0, s3
	s_nop 0
	global_load_lds_dwordx4 v188, s[36:37]
	s_add_i32 m0, s3, 0x2000
	s_nop 0
	global_load_lds_dwordx4 v206, s[36:37]
	s_add_u32 s100, s46, 0x80
	s_addc_u32 s101, s47, 0
	s_mov_b32 m0, s76
	s_nop 0
	global_load_lds_dwordx4 v202, s[100:101]
	s_mov_b32 m0, s77
	s_nop 0
	global_load_lds_dwordx4 v204, s[100:101]
	s_waitcnt vmcnt(8)
	s_waitcnt lgkmcnt(0)
	s_barrier
	s_setprio 1
	s_waitcnt lgkmcnt(0)
	v_mfma_f32_16x16x32_bf16 v[60:63], v[120:123], v[152:155], v[60:63]
	v_mfma_f32_16x16x32_bf16 v[56:59], v[128:131], v[152:155], v[56:59]
	v_mfma_f32_16x16x32_bf16 v[44:47], v[120:123], v[160:163], v[44:47]
	v_mfma_f32_16x16x32_bf16 v[40:43], v[128:131], v[160:163], v[40:43]
	v_mfma_f32_16x16x32_bf16 v[28:31], v[120:123], v[176:179], v[28:31]
	v_mfma_f32_16x16x32_bf16 v[24:27], v[128:131], v[176:179], v[24:27]
	v_mfma_f32_16x16x32_bf16 v[12:15], v[120:123], v[184:187], v[12:15]
	v_mfma_f32_16x16x32_bf16 v[8:11], v[128:131], v[184:187], v[8:11]
	v_mfma_f32_16x16x32_bf16 v[60:63], v[124:127], v[156:159], v[60:63]
	v_mfma_f32_16x16x32_bf16 v[56:59], v[132:135], v[156:159], v[56:59]
	v_mfma_f32_16x16x32_bf16 v[44:47], v[124:127], v[172:175], v[44:47]
	v_mfma_f32_16x16x32_bf16 v[40:43], v[132:135], v[172:175], v[40:43]
	v_mfma_f32_16x16x32_bf16 v[28:31], v[124:127], v[180:183], v[28:31]
	v_mfma_f32_16x16x32_bf16 v[24:27], v[132:135], v[180:183], v[24:27]
	v_mfma_f32_16x16x32_bf16 v[12:15], v[124:127], v[208:211], v[12:15]
	v_mfma_f32_16x16x32_bf16 v[8:11], v[132:135], v[208:211], v[8:11]
	s_setprio 0
	s_setprio 1
	v_mfma_f32_16x16x32_bf16 v[52:55], v[136:139], v[152:155], v[52:55]
	v_mfma_f32_16x16x32_bf16 v[48:51], v[144:147], v[152:155], v[48:51]
	v_mfma_f32_16x16x32_bf16 v[36:39], v[136:139], v[160:163], v[36:39]
	v_mfma_f32_16x16x32_bf16 v[32:35], v[144:147], v[160:163], v[32:35]
	v_mfma_f32_16x16x32_bf16 v[20:23], v[136:139], v[176:179], v[20:23]
	v_mfma_f32_16x16x32_bf16 v[16:19], v[144:147], v[176:179], v[16:19]
	v_mfma_f32_16x16x32_bf16 v[4:7], v[136:139], v[184:187], v[4:7]
	v_mfma_f32_16x16x32_bf16 v[0:3], v[144:147], v[184:187], v[0:3]
	v_mfma_f32_16x16x32_bf16 v[52:55], v[140:143], v[156:159], v[52:55]
	v_mfma_f32_16x16x32_bf16 v[48:51], v[148:151], v[156:159], v[48:51]
	v_mfma_f32_16x16x32_bf16 v[36:39], v[140:143], v[172:175], v[36:39]
	v_mfma_f32_16x16x32_bf16 v[32:35], v[148:151], v[172:175], v[32:35]
	v_mfma_f32_16x16x32_bf16 v[20:23], v[140:143], v[180:183], v[20:23]
	v_mfma_f32_16x16x32_bf16 v[16:19], v[148:151], v[180:183], v[16:19]
	v_mfma_f32_16x16x32_bf16 v[4:7], v[140:143], v[208:211], v[4:7]
	v_mfma_f32_16x16x32_bf16 v[0:3], v[148:151], v[208:211], v[0:3]
	s_setprio 0
	s_barrier
	s_add_i32 s86, s86, 2
	s_cmp_ge_u32 s86, s98
	s_mov_b64 s[36:37], s[38:39]
	s_cbranch_scc1 .Lpeel_exit_resid
.LBB0_490:
	s_add_u32 s38, s36, 0x100
	s_addc_u32 s39, s37, 0
	v_mov_b64_e32 v[120:121], s[24:25]
	v_cmp_ge_u64_e32 vcc, s[38:39], v[120:121]
	s_and_b64 s[46:47], vcc, exec
	s_cselect_b32 s47, s24, 0
	s_cselect_b32 s46, 0, 0
	s_sub_u32 s38, s38, s47
	s_subb_u32 s39, s39, s46
	s_sub_u32 s47, s36, s47
	s_subb_u32 s46, s37, s46
	s_add_u32 vcc_lo, s34, s47
	s_addc_u32 vcc_hi, s35, s46
	s_add_u32 vcc_lo, vcc_lo, 0x100
	s_addc_u32 vcc_hi, vcc_hi, 0
	s_add_u32 s47, s30, s47
	s_addc_u32 s46, s31, s46
	s_add_u32 s69, s47, 0x100
	s_addc_u32 s3, s46, 0
	s_add_i32 s33, 0, 0x10000
	s_cmp_eq_u32 s99, s86
	s_cselect_b32 s47, s11, vcc_hi
	s_cselect_b32 s46, s10, vcc_lo
	s_cselect_b32 vcc_hi, s29, s3
	s_cselect_b32 vcc_lo, s28, s69
	s_add_i32 s3, 0, 0x14000
	v_add_u32_e32 v132, s33, v234
	v_add_u32_e32 v148, s3, v234
	ds_read_b128 v[120:123], v132
	ds_read_b128 v[124:127], v132 offset:1024
	ds_read_b128 v[128:131], v132 offset:2048
	ds_read_b128 v[132:135], v132 offset:3072
	ds_read_b128 v[136:139], v148
	ds_read_b128 v[140:143], v148 offset:1024
	ds_read_b128 v[144:147], v148 offset:2048
	ds_read_b128 v[148:151], v148 offset:3072
	s_add_u32 s36, s0, s36
	s_addc_u32 s37, s43, s37
	s_add_u32 s100, s36, 0x80
	s_addc_u32 s101, s37, 0
	s_add_i32 m0, s94, 0xc000
	ds_read_b128 v[152:155], v248
	ds_read_b128 v[156:159], v248 offset:1024
	ds_read_b128 v[160:163], v248 offset:2048
	ds_read_b128 v[172:175], v248 offset:3072
	ds_read_b128 v[176:179], v248 offset:4096
	ds_read_b128 v[180:183], v248 offset:5120
	ds_read_b128 v[184:187], v248 offset:6144
	ds_read_b128 v[208:211], v248 offset:7168
	global_load_lds_dwordx4 v202, s[100:101]
	s_add_i32 m0, s94, 0xe000
	s_nop 0
	global_load_lds_dwordx4 v204, s[100:101]
	s_waitcnt vmcnt(8)
	s_waitcnt lgkmcnt(0)
	s_barrier
	s_setprio 1
	s_waitcnt lgkmcnt(0)
	v_mfma_f32_16x16x32_bf16 v[168:171], v[120:123], v[152:155], v[168:171]
	v_mfma_f32_16x16x32_bf16 v[164:167], v[128:131], v[152:155], v[164:167]
	v_mfma_f32_16x16x32_bf16 v[108:111], v[120:123], v[160:163], v[108:111]
	v_mfma_f32_16x16x32_bf16 v[104:107], v[128:131], v[160:163], v[104:107]
	v_mfma_f32_16x16x32_bf16 v[92:95], v[120:123], v[176:179], v[92:95]
	v_mfma_f32_16x16x32_bf16 v[88:91], v[128:131], v[176:179], v[88:91]
	v_mfma_f32_16x16x32_bf16 v[76:79], v[120:123], v[184:187], v[76:79]
	v_mfma_f32_16x16x32_bf16 v[72:75], v[128:131], v[184:187], v[72:75]
	v_mfma_f32_16x16x32_bf16 v[168:171], v[124:127], v[156:159], v[168:171]
	v_mfma_f32_16x16x32_bf16 v[164:167], v[132:135], v[156:159], v[164:167]
	v_mfma_f32_16x16x32_bf16 v[108:111], v[124:127], v[172:175], v[108:111]
	v_mfma_f32_16x16x32_bf16 v[104:107], v[132:135], v[172:175], v[104:107]
	v_mfma_f32_16x16x32_bf16 v[92:95], v[124:127], v[180:183], v[92:95]
	v_mfma_f32_16x16x32_bf16 v[88:91], v[132:135], v[180:183], v[88:91]
	v_mfma_f32_16x16x32_bf16 v[76:79], v[124:127], v[208:211], v[76:79]
	v_mfma_f32_16x16x32_bf16 v[72:75], v[132:135], v[208:211], v[72:75]
	s_setprio 0
	s_setprio 1
	v_mfma_f32_16x16x32_bf16 v[116:119], v[136:139], v[152:155], v[116:119]
	v_mfma_f32_16x16x32_bf16 v[112:115], v[144:147], v[152:155], v[112:115]
	v_mfma_f32_16x16x32_bf16 v[100:103], v[136:139], v[160:163], v[100:103]
	v_mfma_f32_16x16x32_bf16 v[96:99], v[144:147], v[160:163], v[96:99]
	v_mfma_f32_16x16x32_bf16 v[84:87], v[136:139], v[176:179], v[84:87]
	v_mfma_f32_16x16x32_bf16 v[80:83], v[144:147], v[176:179], v[80:83]
	v_mfma_f32_16x16x32_bf16 v[68:71], v[136:139], v[184:187], v[68:71]
	v_mfma_f32_16x16x32_bf16 v[64:67], v[144:147], v[184:187], v[64:67]
	v_mfma_f32_16x16x32_bf16 v[116:119], v[140:143], v[156:159], v[116:119]
	v_mfma_f32_16x16x32_bf16 v[112:115], v[148:151], v[156:159], v[112:115]
	v_mfma_f32_16x16x32_bf16 v[100:103], v[140:143], v[172:175], v[100:103]
	v_mfma_f32_16x16x32_bf16 v[96:99], v[148:151], v[172:175], v[96:99]
	v_mfma_f32_16x16x32_bf16 v[84:87], v[140:143], v[180:183], v[84:87]
	v_mfma_f32_16x16x32_bf16 v[80:83], v[148:151], v[180:183], v[80:83]
	v_mfma_f32_16x16x32_bf16 v[68:71], v[140:143], v[208:211], v[68:71]
	v_mfma_f32_16x16x32_bf16 v[64:67], v[148:151], v[208:211], v[64:67]
	s_setprio 0
	s_barrier
	s_add_i32 s33, s33, s89
	s_mov_b64 s[100:101], vcc
	s_mov_b32 m0, s33
	ds_read_b128 v[152:155], v248 offset:16384
	ds_read_b128 v[156:159], v248 offset:17408
	ds_read_b128 v[160:163], v248 offset:18432
	ds_read_b128 v[172:175], v248 offset:19456
	ds_read_b128 v[176:179], v248 offset:20480
	ds_read_b128 v[180:183], v248 offset:21504
	ds_read_b128 v[184:187], v248 offset:22528
	ds_read_b128 v[208:211], v248 offset:23552
	global_load_lds_dwordx4 v188, s[100:101]
	s_add_i32 m0, s33, 0x2000
	s_add_u32 s36, vcc_lo, s92
	s_addc_u32 s37, vcc_hi, 0
	s_add_i32 s3, s3, s89
	global_load_lds_dwordx4 v206, s[100:101]
	s_mov_b32 m0, s3
	s_nop 0
	global_load_lds_dwordx4 v188, s[36:37]
	s_add_i32 m0, s3, 0x2000
	s_nop 0
	global_load_lds_dwordx4 v206, s[36:37]
	s_mov_b32 m0, s94
	s_nop 0
	global_load_lds_dwordx4 v202, s[46:47]
	s_mov_b32 m0, s95
	s_nop 0
	global_load_lds_dwordx4 v204, s[46:47]
	s_waitcnt vmcnt(8)
	s_waitcnt lgkmcnt(0)
	s_barrier
	s_setprio 1
	s_waitcnt lgkmcnt(0)
	v_mfma_f32_16x16x32_bf16 v[60:63], v[120:123], v[152:155], v[60:63]
	v_mfma_f32_16x16x32_bf16 v[56:59], v[128:131], v[152:155], v[56:59]
	v_mfma_f32_16x16x32_bf16 v[44:47], v[120:123], v[160:163], v[44:47]
	v_mfma_f32_16x16x32_bf16 v[40:43], v[128:131], v[160:163], v[40:43]
	v_mfma_f32_16x16x32_bf16 v[28:31], v[120:123], v[176:179], v[28:31]
	v_mfma_f32_16x16x32_bf16 v[24:27], v[128:131], v[176:179], v[24:27]
	v_mfma_f32_16x16x32_bf16 v[12:15], v[120:123], v[184:187], v[12:15]
	v_mfma_f32_16x16x32_bf16 v[8:11], v[128:131], v[184:187], v[8:11]
	v_mfma_f32_16x16x32_bf16 v[60:63], v[124:127], v[156:159], v[60:63]
	v_mfma_f32_16x16x32_bf16 v[56:59], v[132:135], v[156:159], v[56:59]
	v_mfma_f32_16x16x32_bf16 v[44:47], v[124:127], v[172:175], v[44:47]
	v_mfma_f32_16x16x32_bf16 v[40:43], v[132:135], v[172:175], v[40:43]
	v_mfma_f32_16x16x32_bf16 v[28:31], v[124:127], v[180:183], v[28:31]
	v_mfma_f32_16x16x32_bf16 v[24:27], v[132:135], v[180:183], v[24:27]
	v_mfma_f32_16x16x32_bf16 v[12:15], v[124:127], v[208:211], v[12:15]
	v_mfma_f32_16x16x32_bf16 v[8:11], v[132:135], v[208:211], v[8:11]
	s_setprio 0
	s_setprio 1
	v_mfma_f32_16x16x32_bf16 v[52:55], v[136:139], v[152:155], v[52:55]
	v_mfma_f32_16x16x32_bf16 v[48:51], v[144:147], v[152:155], v[48:51]
	v_mfma_f32_16x16x32_bf16 v[36:39], v[136:139], v[160:163], v[36:39]
	v_mfma_f32_16x16x32_bf16 v[32:35], v[144:147], v[160:163], v[32:35]
	v_mfma_f32_16x16x32_bf16 v[20:23], v[136:139], v[176:179], v[20:23]
	v_mfma_f32_16x16x32_bf16 v[16:19], v[144:147], v[176:179], v[16:19]
	v_mfma_f32_16x16x32_bf16 v[4:7], v[136:139], v[184:187], v[4:7]
	v_mfma_f32_16x16x32_bf16 v[0:3], v[144:147], v[184:187], v[0:3]
	v_mfma_f32_16x16x32_bf16 v[52:55], v[140:143], v[156:159], v[52:55]
	v_mfma_f32_16x16x32_bf16 v[48:51], v[148:151], v[156:159], v[48:51]
	v_mfma_f32_16x16x32_bf16 v[36:39], v[140:143], v[172:175], v[36:39]
	v_mfma_f32_16x16x32_bf16 v[32:35], v[148:151], v[172:175], v[32:35]
	v_mfma_f32_16x16x32_bf16 v[20:23], v[140:143], v[180:183], v[20:23]
	v_mfma_f32_16x16x32_bf16 v[16:19], v[148:151], v[180:183], v[16:19]
	v_mfma_f32_16x16x32_bf16 v[4:7], v[140:143], v[208:211], v[4:7]
	v_mfma_f32_16x16x32_bf16 v[0:3], v[148:151], v[208:211], v[0:3]
	s_setprio 0
	s_barrier
	s_add_i32 s3, 0, 0x18000
	s_add_i32 s33, 0, 0x1c000
	v_add_u32_e32 v132, s3, v234
	v_add_u32_e32 v148, s33, v234
	ds_read_b128 v[120:123], v132
	ds_read_b128 v[124:127], v132 offset:1024
	ds_read_b128 v[128:131], v132 offset:2048
	ds_read_b128 v[132:135], v132 offset:3072
	ds_read_b128 v[136:139], v148
	ds_read_b128 v[140:143], v148 offset:1024
	ds_read_b128 v[144:147], v148 offset:2048
	ds_read_b128 v[148:151], v148 offset:3072
	s_add_u32 s36, s46, s92
	s_addc_u32 s37, s47, 0
	s_mov_b32 m0, s96
	ds_read_b128 v[152:155], v248 offset:32768
	ds_read_b128 v[156:159], v248 offset:33792
	ds_read_b128 v[160:163], v248 offset:34816
	ds_read_b128 v[172:175], v248 offset:35840
	ds_read_b128 v[176:179], v248 offset:36864
	ds_read_b128 v[180:183], v248 offset:37888
	ds_read_b128 v[184:187], v248 offset:38912
	ds_read_b128 v[208:211], v248 offset:39936
	global_load_lds_dwordx4 v202, s[36:37]
	s_mov_b32 m0, s97
	s_nop 0
	global_load_lds_dwordx4 v204, s[36:37]
	s_waitcnt vmcnt(8)
	s_waitcnt lgkmcnt(0)
	s_barrier
	s_setprio 1
	s_waitcnt lgkmcnt(0)
	v_mfma_f32_16x16x32_bf16 v[168:171], v[120:123], v[152:155], v[168:171]
	v_mfma_f32_16x16x32_bf16 v[164:167], v[128:131], v[152:155], v[164:167]
	v_mfma_f32_16x16x32_bf16 v[108:111], v[120:123], v[160:163], v[108:111]
	v_mfma_f32_16x16x32_bf16 v[104:107], v[128:131], v[160:163], v[104:107]
	v_mfma_f32_16x16x32_bf16 v[92:95], v[120:123], v[176:179], v[92:95]
	v_mfma_f32_16x16x32_bf16 v[88:91], v[128:131], v[176:179], v[88:91]
	v_mfma_f32_16x16x32_bf16 v[76:79], v[120:123], v[184:187], v[76:79]
	v_mfma_f32_16x16x32_bf16 v[72:75], v[128:131], v[184:187], v[72:75]
	v_mfma_f32_16x16x32_bf16 v[168:171], v[124:127], v[156:159], v[168:171]
	v_mfma_f32_16x16x32_bf16 v[164:167], v[132:135], v[156:159], v[164:167]
	v_mfma_f32_16x16x32_bf16 v[108:111], v[124:127], v[172:175], v[108:111]
	v_mfma_f32_16x16x32_bf16 v[104:107], v[132:135], v[172:175], v[104:107]
	v_mfma_f32_16x16x32_bf16 v[92:95], v[124:127], v[180:183], v[92:95]
	v_mfma_f32_16x16x32_bf16 v[88:91], v[132:135], v[180:183], v[88:91]
	v_mfma_f32_16x16x32_bf16 v[76:79], v[124:127], v[208:211], v[76:79]
	v_mfma_f32_16x16x32_bf16 v[72:75], v[132:135], v[208:211], v[72:75]
	s_setprio 0
	s_setprio 1
	v_mfma_f32_16x16x32_bf16 v[116:119], v[136:139], v[152:155], v[116:119]
	v_mfma_f32_16x16x32_bf16 v[112:115], v[144:147], v[152:155], v[112:115]
	v_mfma_f32_16x16x32_bf16 v[100:103], v[136:139], v[160:163], v[100:103]
	v_mfma_f32_16x16x32_bf16 v[96:99], v[144:147], v[160:163], v[96:99]
	v_mfma_f32_16x16x32_bf16 v[84:87], v[136:139], v[176:179], v[84:87]
	v_mfma_f32_16x16x32_bf16 v[80:83], v[144:147], v[176:179], v[80:83]
	v_mfma_f32_16x16x32_bf16 v[68:71], v[136:139], v[184:187], v[68:71]
	v_mfma_f32_16x16x32_bf16 v[64:67], v[144:147], v[184:187], v[64:67]
	v_mfma_f32_16x16x32_bf16 v[116:119], v[140:143], v[156:159], v[116:119]
	v_mfma_f32_16x16x32_bf16 v[112:115], v[148:151], v[156:159], v[112:115]
	v_mfma_f32_16x16x32_bf16 v[100:103], v[140:143], v[172:175], v[100:103]
	v_mfma_f32_16x16x32_bf16 v[96:99], v[148:151], v[172:175], v[96:99]
	v_mfma_f32_16x16x32_bf16 v[84:87], v[140:143], v[180:183], v[84:87]
	v_mfma_f32_16x16x32_bf16 v[80:83], v[148:151], v[180:183], v[80:83]
	v_mfma_f32_16x16x32_bf16 v[68:71], v[140:143], v[208:211], v[68:71]
	v_mfma_f32_16x16x32_bf16 v[64:67], v[148:151], v[208:211], v[64:67]
	s_setprio 0
	s_barrier
	s_add_i32 s3, s3, s89
	s_add_u32 s100, vcc_lo, 0x80
	s_addc_u32 s101, vcc_hi, 0
	s_mov_b32 m0, s3
	ds_read_b128 v[152:155], v248 offset:49152
	ds_read_b128 v[156:159], v248 offset:50176
	ds_read_b128 v[160:163], v248 offset:51200
	ds_read_b128 v[172:175], v248 offset:52224
	ds_read_b128 v[176:179], v248 offset:53248
	ds_read_b128 v[180:183], v248 offset:54272
	ds_read_b128 v[184:187], v248 offset:55296
	ds_read_b128 v[208:211], v248 offset:56320
	global_load_lds_dwordx4 v188, s[100:101]
	s_add_i32 m0, s3, 0x2000
	s_add_i32 s3, s33, s89
	global_load_lds_dwordx4 v206, s[100:101]
	s_add_u32 s36, s100, s92
	s_addc_u32 s37, s101, 0
	s_mov_b32 m0, s3
	s_nop 0
	global_load_lds_dwordx4 v188, s[36:37]
	s_add_i32 m0, s3, 0x2000
	s_nop 0
	global_load_lds_dwordx4 v206, s[36:37]
	s_add_u32 s100, s46, 0x80
	s_addc_u32 s101, s47, 0
	s_mov_b32 m0, s76
	s_nop 0
	global_load_lds_dwordx4 v202, s[100:101]
	s_mov_b32 m0, s77
	s_nop 0
	global_load_lds_dwordx4 v204, s[100:101]
	s_waitcnt vmcnt(8)
	s_waitcnt lgkmcnt(0)
	s_barrier
	s_setprio 1
	s_waitcnt lgkmcnt(0)
	v_mfma_f32_16x16x32_bf16 v[60:63], v[120:123], v[152:155], v[60:63]
	v_mfma_f32_16x16x32_bf16 v[56:59], v[128:131], v[152:155], v[56:59]
	v_mfma_f32_16x16x32_bf16 v[44:47], v[120:123], v[160:163], v[44:47]
	v_mfma_f32_16x16x32_bf16 v[40:43], v[128:131], v[160:163], v[40:43]
	v_mfma_f32_16x16x32_bf16 v[28:31], v[120:123], v[176:179], v[28:31]
	v_mfma_f32_16x16x32_bf16 v[24:27], v[128:131], v[176:179], v[24:27]
	v_mfma_f32_16x16x32_bf16 v[12:15], v[120:123], v[184:187], v[12:15]
	v_mfma_f32_16x16x32_bf16 v[8:11], v[128:131], v[184:187], v[8:11]
	v_mfma_f32_16x16x32_bf16 v[60:63], v[124:127], v[156:159], v[60:63]
	v_mfma_f32_16x16x32_bf16 v[56:59], v[132:135], v[156:159], v[56:59]
	v_mfma_f32_16x16x32_bf16 v[44:47], v[124:127], v[172:175], v[44:47]
	v_mfma_f32_16x16x32_bf16 v[40:43], v[132:135], v[172:175], v[40:43]
	v_mfma_f32_16x16x32_bf16 v[28:31], v[124:127], v[180:183], v[28:31]
	v_mfma_f32_16x16x32_bf16 v[24:27], v[132:135], v[180:183], v[24:27]
	v_mfma_f32_16x16x32_bf16 v[12:15], v[124:127], v[208:211], v[12:15]
	v_mfma_f32_16x16x32_bf16 v[8:11], v[132:135], v[208:211], v[8:11]
	s_setprio 0
	s_setprio 1
	v_mfma_f32_16x16x32_bf16 v[52:55], v[136:139], v[152:155], v[52:55]
	v_mfma_f32_16x16x32_bf16 v[48:51], v[144:147], v[152:155], v[48:51]
	v_mfma_f32_16x16x32_bf16 v[36:39], v[136:139], v[160:163], v[36:39]
	v_mfma_f32_16x16x32_bf16 v[32:35], v[144:147], v[160:163], v[32:35]
	v_mfma_f32_16x16x32_bf16 v[20:23], v[136:139], v[176:179], v[20:23]
	v_mfma_f32_16x16x32_bf16 v[16:19], v[144:147], v[176:179], v[16:19]
	v_mfma_f32_16x16x32_bf16 v[4:7], v[136:139], v[184:187], v[4:7]
	v_mfma_f32_16x16x32_bf16 v[0:3], v[144:147], v[184:187], v[0:3]
	v_mfma_f32_16x16x32_bf16 v[52:55], v[140:143], v[156:159], v[52:55]
	v_mfma_f32_16x16x32_bf16 v[48:51], v[148:151], v[156:159], v[48:51]
	v_mfma_f32_16x16x32_bf16 v[36:39], v[140:143], v[172:175], v[36:39]
	v_mfma_f32_16x16x32_bf16 v[32:35], v[148:151], v[172:175], v[32:35]
	v_mfma_f32_16x16x32_bf16 v[20:23], v[140:143], v[180:183], v[20:23]
	v_mfma_f32_16x16x32_bf16 v[16:19], v[148:151], v[180:183], v[16:19]
	v_mfma_f32_16x16x32_bf16 v[4:7], v[140:143], v[208:211], v[4:7]
	v_mfma_f32_16x16x32_bf16 v[0:3], v[148:151], v[208:211], v[0:3]
	s_setprio 0
	s_barrier
	s_add_i32 s86, s86, 2
	s_cmp_ge_u32 s86, s98
	s_mov_b64 s[36:37], s[38:39]
	s_cbranch_scc0 .LBB0_490
